# combined: features stage-A load merge + K-loop m0 ordering without s_nop + v_cvt_pk in the retention-output chunk loops, on top of the epilogue weight prefetch version
# baseline (speedup 1.0000x reference)
; #define STAGE(P, BASE, br, kt) STAGET(tid_, P, BASE, br, kt)
; #define LDA(dst, b, h) UFOR(m, 4) UFOR(k, 2) \
;     dst[m][k] = *reinterpret_cast<const bf16x8*>((char*)SA(b, h) + lds_byte(wr * 64 + m * 16 + fr, k * 32 + fq * 8))
; #define LDB(dst, b, h) UFOR(n, 2) UFOR(k, 2) \
;     dst[n][k] = *reinterpret_cast<const bf16x8*>((char*)SB(b, h) + lds_byte(wc * 32 + n * 16 + fr, k * 32 + fq * 8))
; #define MMA(ai, bj, At, Bq) do { __builtin_amdgcn_s_setprio(1); \
;     UFOR(m, 4) UFOR(n, 2) UFOR(k, 2) \
;       acc[ai][bj][m][n] = __builtin_amdgcn_mfma_f32_16x16x32_bf16(Bq[n][k], At[m][k], acc[ai][bj][m][n], 0, 0, 0); \
;     __builtin_amdgcn_s_setprio(0); } while (0)
; #define WAIT_L(n) asm volatile("s_waitcnt lgkmcnt(" #n ")" ::: "memory")
; #define BAR __builtin_amdgcn_s_barrier()
; #define SCHED __builtin_amdgcn_sched_barrier(0)
; template <int EPI, int K, int KL> ...
;     ...
;   for (int t = 0; t < nt - 2; t += 2) {
;     LDB(B0, 0, 0); SCHED; LDA(At, 0, 0); STAGE(SA(1, 1), A, brow + HALF, t + 1);
;     WAIT_L(8); BAR; WAIT_L(0); MMA(0, 0, At, B0); BAR; SCHED;
;     LDB(B1, 0, 1); STAGE(SB(0, 0), Bt, bcol, t + 2);
;     BAR; WAIT_L(0); MMA(0, 1, At, B1); BAR;
;     LDA(At, 0, 1); STAGE(SA(0, 0), A, brow, t + 2);
;     BAR; WAIT_L(0); MMA(1, 0, At, B0); BAR; SCHED;
.LBB0_1107:
	ds_read_b128 v[136:139], v171
	ds_read_b128 v[174:177], v171 offset:1024
	ds_read_b128 v[178:181], v171 offset:2048
	ds_read_b128 v[182:185], v171 offset:3072
	ds_read_b128 v[186:189], v163
	ds_read_b128 v[190:193], v163 offset:1024
	ds_read_b128 v[194:197], v162
	ds_read_b128 v[198:201], v162 offset:1024
	ds_read_b128 v[202:205], v161
	ds_read_b128 v[208:211], v161 offset:1024
	ds_read_b128 v[218:221], v160
	ds_read_b128 v[222:225], v160 offset:1024
	v_add_u32_e32 v172, 0xc000, v158
	v_lshl_add_u64 v[214:215], s[92:93], 0, v[148:149]
	v_readfirstlane_b32 s56, v172
	v_lshl_add_u64 v[216:217], v[214:215], 0, s[88:89]
	s_mov_b32 m0, s56
	v_add_u32_e32 v173, 0xe000, v158
	global_load_lds_dwordx4 v[216:217], off
	v_lshl_add_u64 v[216:217], s[92:93], 0, v[150:151]
	v_readfirstlane_b32 s56, v173
	s_mov_b32 m0, s56
	v_lshl_add_u64 v[226:227], v[216:217], 0, s[88:89]
	global_load_lds_dwordx4 v[226:227], off
	s_waitcnt lgkmcnt(8)
	s_barrier
	s_waitcnt lgkmcnt(0)
	s_waitcnt lgkmcnt(0)
	v_mfma_f32_16x16x32_bf16 v[0:3], v[136:139], v[186:189], v[0:3]
	v_mfma_f32_16x16x32_bf16 v[4:7], v[178:181], v[186:189], v[4:7]
	v_mfma_f32_16x16x32_bf16 v[8:11], v[136:139], v[194:197], v[8:11]
	v_mfma_f32_16x16x32_bf16 v[16:19], v[178:181], v[194:197], v[16:19]
	v_mfma_f32_16x16x32_bf16 v[28:31], v[136:139], v[202:205], v[28:31]
	v_mfma_f32_16x16x32_bf16 v[40:43], v[178:181], v[202:205], v[40:43]
	v_mfma_f32_16x16x32_bf16 v[52:55], v[136:139], v[218:221], v[52:55]
	v_mfma_f32_16x16x32_bf16 v[64:67], v[178:181], v[218:221], v[64:67]
	v_mfma_f32_16x16x32_bf16 v[0:3], v[174:177], v[190:193], v[0:3]
	v_mfma_f32_16x16x32_bf16 v[4:7], v[182:185], v[190:193], v[4:7]
	v_mfma_f32_16x16x32_bf16 v[8:11], v[174:177], v[198:201], v[8:11]
	v_mfma_f32_16x16x32_bf16 v[16:19], v[182:185], v[198:201], v[16:19]
	v_mfma_f32_16x16x32_bf16 v[28:31], v[174:177], v[208:211], v[28:31]
	v_mfma_f32_16x16x32_bf16 v[40:43], v[182:185], v[208:211], v[40:43]
	v_mfma_f32_16x16x32_bf16 v[52:55], v[174:177], v[222:225], v[52:55]
	v_mfma_f32_16x16x32_bf16 v[64:67], v[182:185], v[222:225], v[64:67]
	s_barrier
	ds_read_b128 v[226:229], v169
	ds_read_b128 v[230:233], v169 offset:1024
	ds_read_b128 v[234:237], v169 offset:2048
	ds_read_b128 v[238:241], v169 offset:3072
	v_lshl_add_u64 v[242:243], s[92:93], 0, v[144:145]
	v_readfirstlane_b32 s56, v157
	v_lshl_add_u64 v[244:245], v[242:243], 0, s[2:3]
	s_mov_b32 m0, s56
	v_add_u32_e32 v134, 0x2000, v157
	global_load_lds_dwordx4 v[244:245], off
	v_lshl_add_u64 v[244:245], s[92:93], 0, v[146:147]
	v_readfirstlane_b32 s56, v134
	s_mov_b32 m0, s56
	v_lshl_add_u64 v[246:247], v[244:245], 0, s[2:3]
	global_load_lds_dwordx4 v[246:247], off
	s_barrier
	s_waitcnt lgkmcnt(0)
	s_waitcnt lgkmcnt(0)
	v_mfma_f32_16x16x32_bf16 v[12:15], v[226:229], v[186:189], v[12:15]
	v_mfma_f32_16x16x32_bf16 v[24:27], v[234:237], v[186:189], v[24:27]
	v_mfma_f32_16x16x32_bf16 v[36:39], v[226:229], v[194:197], v[36:39]
	v_mfma_f32_16x16x32_bf16 v[48:51], v[234:237], v[194:197], v[48:51]
	v_mfma_f32_16x16x32_bf16 v[60:63], v[226:229], v[202:205], v[60:63]
	v_mfma_f32_16x16x32_bf16 v[72:75], v[234:237], v[202:205], v[72:75]
	v_mfma_f32_16x16x32_bf16 v[80:83], v[226:229], v[218:221], v[80:83]
	v_mfma_f32_16x16x32_bf16 v[88:91], v[234:237], v[218:221], v[88:91]
	v_mfma_f32_16x16x32_bf16 v[12:15], v[230:233], v[190:193], v[12:15]
	v_mfma_f32_16x16x32_bf16 v[24:27], v[238:241], v[190:193], v[24:27]
	v_mfma_f32_16x16x32_bf16 v[36:39], v[230:233], v[198:201], v[36:39]
	v_mfma_f32_16x16x32_bf16 v[48:51], v[238:241], v[198:201], v[48:51]
	v_mfma_f32_16x16x32_bf16 v[60:63], v[230:233], v[208:211], v[60:63]
	v_mfma_f32_16x16x32_bf16 v[72:75], v[238:241], v[208:211], v[72:75]
	v_mfma_f32_16x16x32_bf16 v[80:83], v[230:233], v[222:225], v[80:83]
	v_mfma_f32_16x16x32_bf16 v[88:91], v[238:241], v[222:225], v[88:91]
	v_readfirstlane_b32 s56, v158
	v_add_u32_e32 v134, 0x2000, v158
	v_lshl_add_u64 v[246:247], v[214:215], 0, s[8:9]
	s_mov_b32 m0, s56
	v_readfirstlane_b32 s56, v134
	s_barrier
	ds_read_b128 v[186:189], v163 offset:16384
	ds_read_b128 v[190:193], v163 offset:17408
	ds_read_b128 v[194:197], v162 offset:16384
	ds_read_b128 v[198:201], v162 offset:17408
	ds_read_b128 v[202:205], v161 offset:16384
	ds_read_b128 v[208:211], v161 offset:17408
	ds_read_b128 v[218:221], v160 offset:16384
	ds_read_b128 v[222:225], v160 offset:17408
	global_load_lds_dwordx4 v[246:247], off
	s_mov_b32 m0, s56
	v_lshl_add_u64 v[246:247], v[216:217], 0, s[8:9]
	global_load_lds_dwordx4 v[246:247], off
	s_barrier
	s_waitcnt lgkmcnt(0)
	s_waitcnt lgkmcnt(0)
	v_mfma_f32_16x16x32_bf16 v[20:23], v[136:139], v[186:189], v[20:23]
	v_mfma_f32_16x16x32_bf16 v[32:35], v[178:181], v[186:189], v[32:35]
	v_mfma_f32_16x16x32_bf16 v[44:47], v[136:139], v[194:197], v[44:47]
	v_mfma_f32_16x16x32_bf16 v[56:59], v[178:181], v[194:197], v[56:59]
	v_mfma_f32_16x16x32_bf16 v[68:71], v[136:139], v[202:205], v[68:71]
	v_mfma_f32_16x16x32_bf16 v[76:79], v[178:181], v[202:205], v[76:79]
	v_mfma_f32_16x16x32_bf16 v[84:87], v[136:139], v[218:221], v[84:87]
	v_mfma_f32_16x16x32_bf16 v[92:95], v[178:181], v[218:221], v[92:95]
	v_mfma_f32_16x16x32_bf16 v[20:23], v[174:177], v[190:193], v[20:23]
	v_mfma_f32_16x16x32_bf16 v[32:35], v[182:185], v[190:193], v[32:35]
	v_mfma_f32_16x16x32_bf16 v[44:47], v[174:177], v[198:201], v[44:47]
	v_mfma_f32_16x16x32_bf16 v[56:59], v[182:185], v[198:201], v[56:59]
	v_mfma_f32_16x16x32_bf16 v[68:71], v[174:177], v[208:211], v[68:71]
	v_mfma_f32_16x16x32_bf16 v[76:79], v[182:185], v[208:211], v[76:79]
	v_mfma_f32_16x16x32_bf16 v[84:87], v[174:177], v[222:225], v[84:87]
	v_mfma_f32_16x16x32_bf16 v[92:95], v[182:185], v[222:225], v[92:95]
	s_barrier
; #define STAGE(P, BASE, br, kt) STAGET(tid_, P, BASE, br, kt)
; #define LDA(dst, b, h) UFOR(m, 4) UFOR(k, 2) \
;     dst[m][k] = *reinterpret_cast<const bf16x8*>((char*)SA(b, h) + lds_byte(wr * 64 + m * 16 + fr, k * 32 + fq * 8))
; #define LDB(dst, b, h) UFOR(n, 2) UFOR(k, 2) \
;     dst[n][k] = *reinterpret_cast<const bf16x8*>((char*)SB(b, h) + lds_byte(wc * 32 + n * 16 + fr, k * 32 + fq * 8))
; #define MMA(ai, bj, At, Bq) do { __builtin_amdgcn_s_setprio(1); \
;     UFOR(m, 4) UFOR(n, 2) UFOR(k, 2) \
;       acc[ai][bj][m][n] = __builtin_amdgcn_mfma_f32_16x16x32_bf16(Bq[n][k], At[m][k], acc[ai][bj][m][n], 0, 0, 0); \
;     __builtin_amdgcn_s_setprio(0); } while (0)
; #define WAIT_V(n) asm volatile("s_waitcnt vmcnt(" #n ")" ::: "memory")
; #define WAIT_L(n) asm volatile("s_waitcnt lgkmcnt(" #n ")" ::: "memory")
; #define BAR __builtin_amdgcn_s_barrier()
; #define SCHED __builtin_amdgcn_sched_barrier(0)
; template <int EPI, int K, int KL> ...
;     ...
;     STAGE(SB(0, 1), Bt, bcol + HALF, t + 2);
;     WAIT_V(6); BAR; MMA(1, 1, At, B1); BAR;
;     LDB(B0, 1, 0); SCHED; LDA(At, 1, 0); STAGE(SA(0, 1), A, brow + HALF, t + 2);
;     WAIT_L(8); BAR; WAIT_L(0); MMA(0, 0, At, B0); BAR; SCHED;
;     LDB(B1, 1, 1); STAGE(SB(1, 0), Bt, bcol, t + 3);
;     BAR; WAIT_L(0); MMA(0, 1, At, B1); BAR;
;     LDA(At, 1, 1); STAGE(SA(1, 0), A, brow, t + 3);
	v_readfirstlane_b32 s56, v159
	v_add_u32_e32 v134, 0x2000, v159
	v_lshl_add_u64 v[136:137], v[242:243], 0, s[96:97]
	s_mov_b32 m0, s56
	v_readfirstlane_b32 s56, v134
	global_load_lds_dwordx4 v[136:137], off
	s_mov_b32 m0, s56
	v_lshl_add_u64 v[136:137], v[244:245], 0, s[96:97]
	global_load_lds_dwordx4 v[136:137], off
	s_waitcnt vmcnt(6)
	s_barrier
	v_mfma_f32_16x16x32_bf16 v[96:99], v[226:229], v[186:189], v[96:99]
	v_mfma_f32_16x16x32_bf16 v[100:103], v[234:237], v[186:189], v[100:103]
	v_mfma_f32_16x16x32_bf16 v[104:107], v[226:229], v[194:197], v[104:107]
	v_mfma_f32_16x16x32_bf16 v[108:111], v[234:237], v[194:197], v[108:111]
	v_mfma_f32_16x16x32_bf16 v[112:115], v[226:229], v[202:205], v[112:115]
	v_mfma_f32_16x16x32_bf16 v[116:119], v[234:237], v[202:205], v[116:119]
	v_mfma_f32_16x16x32_bf16 v[120:123], v[226:229], v[218:221], v[120:123]
	v_mfma_f32_16x16x32_bf16 v[124:127], v[234:237], v[218:221], v[124:127]
	v_mfma_f32_16x16x32_bf16 v[96:99], v[230:233], v[190:193], v[96:99]
	v_mfma_f32_16x16x32_bf16 v[100:103], v[238:241], v[190:193], v[100:103]
	v_mfma_f32_16x16x32_bf16 v[104:107], v[230:233], v[198:201], v[104:107]
	v_mfma_f32_16x16x32_bf16 v[108:111], v[238:241], v[198:201], v[108:111]
	v_mfma_f32_16x16x32_bf16 v[112:115], v[230:233], v[208:211], v[112:115]
	v_mfma_f32_16x16x32_bf16 v[116:119], v[238:241], v[208:211], v[116:119]
	v_mfma_f32_16x16x32_bf16 v[120:123], v[230:233], v[222:225], v[120:123]
	v_mfma_f32_16x16x32_bf16 v[124:127], v[238:241], v[222:225], v[124:127]
	s_barrier
	ds_read_b128 v[136:139], v166
	ds_read_b128 v[174:177], v166 offset:1024
	ds_read_b128 v[178:181], v166 offset:2048
	ds_read_b128 v[182:185], v166 offset:3072
	ds_read_b128 v[186:189], v163 offset:32768
	ds_read_b128 v[190:193], v163 offset:33792
	ds_read_b128 v[194:197], v162 offset:32768
	ds_read_b128 v[198:201], v162 offset:33792
	ds_read_b128 v[202:205], v161 offset:32768
	ds_read_b128 v[208:211], v161 offset:33792
	ds_read_b128 v[218:221], v160 offset:32768
	ds_read_b128 v[222:225], v160 offset:33792
	v_add_u32_e32 v134, 0x4000, v158
	v_lshl_add_u64 v[226:227], v[214:215], 0, s[12:13]
	v_readfirstlane_b32 s56, v134
	v_add_u32_e32 v134, 0x6000, v158
	s_mov_b32 m0, s56
	v_readfirstlane_b32 s56, v134
	global_load_lds_dwordx4 v[226:227], off
	s_mov_b32 m0, s56
	v_lshl_add_u64 v[226:227], v[216:217], 0, s[12:13]
	global_load_lds_dwordx4 v[226:227], off
	s_waitcnt lgkmcnt(8)
	s_barrier
	s_waitcnt lgkmcnt(0)
	s_waitcnt lgkmcnt(0)
	v_mfma_f32_16x16x32_bf16 v[0:3], v[136:139], v[186:189], v[0:3]
	v_mfma_f32_16x16x32_bf16 v[4:7], v[178:181], v[186:189], v[4:7]
	v_mfma_f32_16x16x32_bf16 v[8:11], v[136:139], v[194:197], v[8:11]
	v_mfma_f32_16x16x32_bf16 v[16:19], v[178:181], v[194:197], v[16:19]
	v_mfma_f32_16x16x32_bf16 v[28:31], v[136:139], v[202:205], v[28:31]
	v_mfma_f32_16x16x32_bf16 v[40:43], v[178:181], v[202:205], v[40:43]
	v_mfma_f32_16x16x32_bf16 v[52:55], v[136:139], v[218:221], v[52:55]
	v_mfma_f32_16x16x32_bf16 v[64:67], v[178:181], v[218:221], v[64:67]
	v_mfma_f32_16x16x32_bf16 v[0:3], v[174:177], v[190:193], v[0:3]
	v_mfma_f32_16x16x32_bf16 v[4:7], v[182:185], v[190:193], v[4:7]
	v_mfma_f32_16x16x32_bf16 v[8:11], v[174:177], v[198:201], v[8:11]
	v_mfma_f32_16x16x32_bf16 v[16:19], v[182:185], v[198:201], v[16:19]
	v_mfma_f32_16x16x32_bf16 v[28:31], v[174:177], v[208:211], v[28:31]
	v_mfma_f32_16x16x32_bf16 v[40:43], v[182:185], v[208:211], v[40:43]
	v_mfma_f32_16x16x32_bf16 v[52:55], v[174:177], v[222:225], v[52:55]
	v_mfma_f32_16x16x32_bf16 v[64:67], v[182:185], v[222:225], v[64:67]
	s_barrier
	ds_read_b128 v[226:229], v164
	ds_read_b128 v[230:233], v164 offset:1024
	ds_read_b128 v[234:237], v164 offset:2048
	ds_read_b128 v[238:241], v164 offset:3072
	v_readfirstlane_b32 s56, v165
	v_add_u32_e32 v134, 0x2000, v165
	v_lshl_add_u64 v[246:247], v[242:243], 0, s[80:81]
	s_mov_b32 m0, s56
	v_readfirstlane_b32 s56, v134
	global_load_lds_dwordx4 v[246:247], off
	s_mov_b32 m0, s56
	v_lshl_add_u64 v[246:247], v[244:245], 0, s[80:81]
	global_load_lds_dwordx4 v[246:247], off
	s_barrier
	s_waitcnt lgkmcnt(0)
	s_waitcnt lgkmcnt(0)
	v_mfma_f32_16x16x32_bf16 v[12:15], v[226:229], v[186:189], v[12:15]
	v_mfma_f32_16x16x32_bf16 v[24:27], v[234:237], v[186:189], v[24:27]
	v_mfma_f32_16x16x32_bf16 v[36:39], v[226:229], v[194:197], v[36:39]
	v_mfma_f32_16x16x32_bf16 v[48:51], v[234:237], v[194:197], v[48:51]
	v_mfma_f32_16x16x32_bf16 v[60:63], v[226:229], v[202:205], v[60:63]
	v_mfma_f32_16x16x32_bf16 v[72:75], v[234:237], v[202:205], v[72:75]
	v_mfma_f32_16x16x32_bf16 v[80:83], v[226:229], v[218:221], v[80:83]
	v_mfma_f32_16x16x32_bf16 v[88:91], v[234:237], v[218:221], v[88:91]
	v_mfma_f32_16x16x32_bf16 v[12:15], v[230:233], v[190:193], v[12:15]
	v_mfma_f32_16x16x32_bf16 v[24:27], v[238:241], v[190:193], v[24:27]
	v_mfma_f32_16x16x32_bf16 v[36:39], v[230:233], v[198:201], v[36:39]
	v_mfma_f32_16x16x32_bf16 v[48:51], v[238:241], v[198:201], v[48:51]
	v_mfma_f32_16x16x32_bf16 v[60:63], v[230:233], v[208:211], v[60:63]
	v_mfma_f32_16x16x32_bf16 v[72:75], v[238:241], v[208:211], v[72:75]
	v_mfma_f32_16x16x32_bf16 v[80:83], v[230:233], v[222:225], v[80:83]
	v_mfma_f32_16x16x32_bf16 v[88:91], v[238:241], v[222:225], v[88:91]
	v_readfirstlane_b32 s56, v167
	v_lshl_add_u64 v[214:215], v[214:215], 0, s[16:17]
	s_mov_b32 m0, s56
	v_readfirstlane_b32 s56, v168
	s_barrier
	ds_read_b128 v[186:189], v163 offset:49152
	ds_read_b128 v[190:193], v163 offset:50176
	ds_read_b128 v[194:197], v162 offset:49152
	ds_read_b128 v[198:201], v162 offset:50176
	ds_read_b128 v[202:205], v161 offset:49152
	ds_read_b128 v[208:211], v161 offset:50176
	ds_read_b128 v[218:221], v160 offset:49152
	ds_read_b128 v[222:225], v160 offset:50176
	global_load_lds_dwordx4 v[214:215], off
	s_mov_b32 m0, s56
	v_lshl_add_u64 v[214:215], v[216:217], 0, s[16:17]
	global_load_lds_dwordx4 v[214:215], off
	s_barrier
; #define STAGE(P, BASE, br, kt) STAGET(tid_, P, BASE, br, kt)
; #define LDA(dst, b, h) UFOR(m, 4) UFOR(k, 2) \
;     dst[m][k] = *reinterpret_cast<const bf16x8*>((char*)SA(b, h) + lds_byte(wr * 64 + m * 16 + fr, k * 32 + fq * 8))
; #define LDB(dst, b, h) UFOR(n, 2) UFOR(k, 2) \
;     dst[n][k] = *reinterpret_cast<const bf16x8*>((char*)SB(b, h) + lds_byte(wc * 32 + n * 16 + fr, k * 32 + fq * 8))
; #define MMA(ai, bj, At, Bq) do { __builtin_amdgcn_s_setprio(1); \
;     UFOR(m, 4) UFOR(n, 2) UFOR(k, 2) \
;       acc[ai][bj][m][n] = __builtin_amdgcn_mfma_f32_16x16x32_bf16(Bq[n][k], At[m][k], acc[ai][bj][m][n], 0, 0, 0); \
;     __builtin_amdgcn_s_setprio(0); } while (0)
; #define WAIT_V(n) asm volatile("s_waitcnt vmcnt(" #n ")" ::: "memory")
; #define WAIT_L(n) asm volatile("s_waitcnt lgkmcnt(" #n ")" ::: "memory")
; #define BAR __builtin_amdgcn_s_barrier()
; #define SCHED __builtin_amdgcn_sched_barrier(0)
; template <int EPI, int K, int KL> ...
;     ...
;     BAR; WAIT_L(0); MMA(1, 0, At, B0); BAR; SCHED;
;     STAGE(SB(1, 1), Bt, bcol + HALF, t + 3);
;     WAIT_V(6); BAR; MMA(1, 1, At, B1); BAR;
;   }
;   { LDB(B0, 0, 0); LDA(At, 0, 0); STAGE(SA(1, 1), A, brow + HALF, nt - 1);
;     BAR; WAIT_L(0); MMA(0, 0, At, B0); BAR;
;     LDB(B1, 0, 1); BAR; WAIT_L(0); MMA(0, 1, At, B1); BAR;
	s_waitcnt lgkmcnt(0)
	s_waitcnt lgkmcnt(0)
	v_mfma_f32_16x16x32_bf16 v[20:23], v[136:139], v[186:189], v[20:23]
	v_mfma_f32_16x16x32_bf16 v[32:35], v[178:181], v[186:189], v[32:35]
	v_mfma_f32_16x16x32_bf16 v[44:47], v[136:139], v[194:197], v[44:47]
	v_mfma_f32_16x16x32_bf16 v[56:59], v[178:181], v[194:197], v[56:59]
	v_mfma_f32_16x16x32_bf16 v[68:71], v[136:139], v[202:205], v[68:71]
	v_mfma_f32_16x16x32_bf16 v[76:79], v[178:181], v[202:205], v[76:79]
	v_mfma_f32_16x16x32_bf16 v[84:87], v[136:139], v[218:221], v[84:87]
	v_mfma_f32_16x16x32_bf16 v[92:95], v[178:181], v[218:221], v[92:95]
	v_mfma_f32_16x16x32_bf16 v[20:23], v[174:177], v[190:193], v[20:23]
	v_mfma_f32_16x16x32_bf16 v[32:35], v[182:185], v[190:193], v[32:35]
	v_mfma_f32_16x16x32_bf16 v[44:47], v[174:177], v[198:201], v[44:47]
	v_mfma_f32_16x16x32_bf16 v[56:59], v[182:185], v[198:201], v[56:59]
	v_mfma_f32_16x16x32_bf16 v[68:71], v[174:177], v[208:211], v[68:71]
	v_mfma_f32_16x16x32_bf16 v[76:79], v[182:185], v[208:211], v[76:79]
	v_mfma_f32_16x16x32_bf16 v[84:87], v[174:177], v[222:225], v[84:87]
	v_mfma_f32_16x16x32_bf16 v[92:95], v[182:185], v[222:225], v[92:95]
	s_barrier
	v_readfirstlane_b32 s56, v170
	v_add_u32_e32 v134, 0x2000, v170
	v_lshl_add_u64 v[136:137], v[242:243], 0, s[90:91]
	s_mov_b32 m0, s56
	v_readfirstlane_b32 s56, v134
	global_load_lds_dwordx4 v[136:137], off
	s_mov_b32 m0, s56
	v_lshl_add_u64 v[136:137], v[244:245], 0, s[90:91]
	global_load_lds_dwordx4 v[136:137], off
	s_waitcnt vmcnt(6)
	s_barrier
	v_mfma_f32_16x16x32_bf16 v[96:99], v[226:229], v[186:189], v[96:99]
	v_mfma_f32_16x16x32_bf16 v[100:103], v[234:237], v[186:189], v[100:103]
	v_mfma_f32_16x16x32_bf16 v[104:107], v[226:229], v[194:197], v[104:107]
	v_mfma_f32_16x16x32_bf16 v[108:111], v[234:237], v[194:197], v[108:111]
	v_mfma_f32_16x16x32_bf16 v[112:115], v[226:229], v[202:205], v[112:115]
	v_mfma_f32_16x16x32_bf16 v[116:119], v[234:237], v[202:205], v[116:119]
	v_mfma_f32_16x16x32_bf16 v[120:123], v[226:229], v[218:221], v[120:123]
	v_mfma_f32_16x16x32_bf16 v[124:127], v[234:237], v[218:221], v[124:127]
	v_mfma_f32_16x16x32_bf16 v[96:99], v[230:233], v[190:193], v[96:99]
	v_mfma_f32_16x16x32_bf16 v[100:103], v[238:241], v[190:193], v[100:103]
	v_mfma_f32_16x16x32_bf16 v[104:107], v[230:233], v[198:201], v[104:107]
	v_mfma_f32_16x16x32_bf16 v[108:111], v[238:241], v[198:201], v[108:111]
	v_mfma_f32_16x16x32_bf16 v[112:115], v[230:233], v[208:211], v[112:115]
	v_mfma_f32_16x16x32_bf16 v[116:119], v[238:241], v[208:211], v[116:119]
	v_mfma_f32_16x16x32_bf16 v[120:123], v[230:233], v[222:225], v[120:123]
	v_mfma_f32_16x16x32_bf16 v[124:127], v[238:241], v[222:225], v[124:127]
	s_add_i32 s53, s53, 2
	v_lshl_add_u64 v[144:145], v[144:145], 0, s[20:21]
	v_lshl_add_u64 v[146:147], v[146:147], 0, s[20:21]
	v_lshl_add_u64 v[148:149], v[148:149], 0, s[20:21]
	s_cmp_lt_u32 s53, 28
	v_lshl_add_u64 v[150:151], v[150:151], 0, s[20:21]
	s_cbranch_scc1 .Lkrot_1107
	s_barrier
	s_add_u32 s40, s40, 0x80f80
	s_addc_u32 s41, s41, 0
	v_lshl_add_u64 v[130:131], s[40:41], 0, v[130:131]
	v_readfirstlane_b32 s53, v172
	v_lshl_add_u64 v[128:129], v[128:129], 1, v[130:131]
	s_mov_b32 m0, s53
	ds_read_b128 v[136:139], v171
	ds_read_b128 v[144:147], v171 offset:1024
	ds_read_b128 v[148:151], v171 offset:2048
	ds_read_b128 v[174:177], v171 offset:3072
	ds_read_b128 v[178:181], v163
	ds_read_b128 v[182:185], v163 offset:1024
	ds_read_b128 v[186:189], v162
	ds_read_b128 v[190:193], v162 offset:1024
	ds_read_b128 v[194:197], v161
	ds_read_b128 v[198:201], v161 offset:1024
	ds_read_b128 v[202:205], v160
	ds_read_b128 v[208:211], v160 offset:1024
	global_load_lds_dwordx4 v[128:129], off
	v_lshl_add_u64 v[128:129], s[40:41], 0, v[142:143]
	v_readfirstlane_b32 s40, v173
	v_lshl_add_u64 v[128:129], v[140:141], 1, v[128:129]
	s_mov_b32 m0, s40
	s_nop 0
	global_load_lds_dwordx4 v[128:129], off
	s_barrier
	s_waitcnt lgkmcnt(0)
	s_waitcnt lgkmcnt(0)
	v_mfma_f32_16x16x32_bf16 v[0:3], v[136:139], v[178:181], v[0:3]
	v_mfma_f32_16x16x32_bf16 v[4:7], v[148:151], v[178:181], v[4:7]
	v_mfma_f32_16x16x32_bf16 v[8:11], v[136:139], v[186:189], v[8:11]
	v_mfma_f32_16x16x32_bf16 v[16:19], v[148:151], v[186:189], v[16:19]
	v_mfma_f32_16x16x32_bf16 v[28:31], v[136:139], v[194:197], v[28:31]
	v_mfma_f32_16x16x32_bf16 v[40:43], v[148:151], v[194:197], v[40:43]
	v_mfma_f32_16x16x32_bf16 v[52:55], v[136:139], v[202:205], v[52:55]
	v_mfma_f32_16x16x32_bf16 v[64:67], v[148:151], v[202:205], v[64:67]
	v_mfma_f32_16x16x32_bf16 v[0:3], v[144:147], v[182:185], v[0:3]
	v_mfma_f32_16x16x32_bf16 v[4:7], v[174:177], v[182:185], v[4:7]
	v_mfma_f32_16x16x32_bf16 v[8:11], v[144:147], v[190:193], v[8:11]
	v_mfma_f32_16x16x32_bf16 v[16:19], v[174:177], v[190:193], v[16:19]
	v_mfma_f32_16x16x32_bf16 v[28:31], v[144:147], v[198:201], v[28:31]
	v_mfma_f32_16x16x32_bf16 v[40:43], v[174:177], v[198:201], v[40:43]
	v_mfma_f32_16x16x32_bf16 v[52:55], v[144:147], v[208:211], v[52:55]
	v_mfma_f32_16x16x32_bf16 v[64:67], v[174:177], v[208:211], v[64:67]
	s_barrier
	ds_read_b128 v[128:131], v169
	ds_read_b128 v[140:143], v169 offset:1024
	ds_read_b128 v[170:173], v169 offset:2048
	ds_read_b128 v[218:221], v169 offset:3072
	s_barrier
; #define LDA(dst, b, h) UFOR(m, 4) UFOR(k, 2) \
;     dst[m][k] = *reinterpret_cast<const bf16x8*>((char*)SA(b, h) + lds_byte(wr * 64 + m * 16 + fr, k * 32 + fq * 8))
; #define LDB(dst, b, h) UFOR(n, 2) UFOR(k, 2) \
;     dst[n][k] = *reinterpret_cast<const bf16x8*>((char*)SB(b, h) + lds_byte(wc * 32 + n * 16 + fr, k * 32 + fq * 8))
; #define MMA(ai, bj, At, Bq) do { __builtin_amdgcn_s_setprio(1); \
;     UFOR(m, 4) UFOR(n, 2) UFOR(k, 2) \
;       acc[ai][bj][m][n] = __builtin_amdgcn_mfma_f32_16x16x32_bf16(Bq[n][k], At[m][k], acc[ai][bj][m][n], 0, 0, 0); \
;     __builtin_amdgcn_s_setprio(0); } while (0)
; #define WAIT_V(n) asm volatile("s_waitcnt vmcnt(" #n ")" ::: "memory")
; #define WAIT_L(n) asm volatile("s_waitcnt lgkmcnt(" #n ")" ::: "memory")
; #define BAR __builtin_amdgcn_s_barrier()
; template <int EPI, int K, int KL> ...
;     ...
;     LDB(B1, 0, 1); BAR; WAIT_L(0); MMA(0, 1, At, B1); BAR;
;     LDA(At, 0, 1); WAIT_V(4); BAR; WAIT_L(0); MMA(1, 0, At, B0); MMA(1, 1, At, B1); BAR; }
;   { LDB(B0, 1, 0); LDA(At, 1, 0); WAIT_V(2); BAR; WAIT_L(0); MMA(0, 0, At, B0); BAR;
	s_waitcnt lgkmcnt(0)
	s_waitcnt lgkmcnt(0)
	v_mfma_f32_16x16x32_bf16 v[12:15], v[128:131], v[178:181], v[12:15]
	v_mfma_f32_16x16x32_bf16 v[24:27], v[170:173], v[178:181], v[24:27]
	v_mfma_f32_16x16x32_bf16 v[36:39], v[128:131], v[186:189], v[36:39]
	v_mfma_f32_16x16x32_bf16 v[48:51], v[170:173], v[186:189], v[48:51]
	v_mfma_f32_16x16x32_bf16 v[60:63], v[128:131], v[194:197], v[60:63]
	v_mfma_f32_16x16x32_bf16 v[72:75], v[170:173], v[194:197], v[72:75]
	v_mfma_f32_16x16x32_bf16 v[80:83], v[128:131], v[202:205], v[80:83]
	v_mfma_f32_16x16x32_bf16 v[12:15], v[140:143], v[182:185], v[12:15]
	v_mfma_f32_16x16x32_bf16 v[24:27], v[218:221], v[182:185], v[24:27]
	v_mfma_f32_16x16x32_bf16 v[36:39], v[140:143], v[190:193], v[36:39]
	v_mfma_f32_16x16x32_bf16 v[48:51], v[218:221], v[190:193], v[48:51]
	v_mfma_f32_16x16x32_bf16 v[60:63], v[140:143], v[198:201], v[60:63]
	v_mfma_f32_16x16x32_bf16 v[72:75], v[218:221], v[198:201], v[72:75]
	v_mfma_f32_16x16x32_bf16 v[178:181], v[140:143], v[208:211], v[80:83]
	v_mfma_f32_16x16x32_bf16 v[80:83], v[170:173], v[202:205], v[88:91]
	v_mfma_f32_16x16x32_bf16 v[182:185], v[218:221], v[208:211], v[80:83]
	s_barrier
	s_nop 5
	ds_read_b128 v[80:83], v163 offset:16384
	ds_read_b128 v[88:91], v163 offset:17408
	ds_read_b128 v[186:189], v162 offset:16384
	ds_read_b128 v[190:193], v162 offset:17408
	ds_read_b128 v[194:197], v161 offset:16384
	ds_read_b128 v[198:201], v161 offset:17408
	ds_read_b128 v[202:205], v160 offset:16384
	ds_read_b128 v[208:211], v160 offset:17408
	s_waitcnt vmcnt(4)
	s_barrier
	s_waitcnt lgkmcnt(0)
	s_waitcnt lgkmcnt(0)
	v_mfma_f32_16x16x32_bf16 v[56:59], v[148:151], v[186:189], v[56:59]
	v_mfma_f32_16x16x32_bf16 v[222:225], v[174:177], v[190:193], v[56:59]
	v_mfma_f32_16x16x32_bf16 v[56:59], v[136:139], v[194:197], v[68:71]
	v_mfma_f32_16x16x32_bf16 v[226:229], v[144:147], v[198:201], v[56:59]
	v_mfma_f32_16x16x32_bf16 v[56:59], v[148:151], v[194:197], v[76:79]
	v_mfma_f32_16x16x32_bf16 v[20:23], v[136:139], v[80:83], v[20:23]
	v_mfma_f32_16x16x32_bf16 v[32:35], v[148:151], v[80:83], v[32:35]
	v_mfma_f32_16x16x32_bf16 v[44:47], v[136:139], v[186:189], v[44:47]
	v_mfma_f32_16x16x32_bf16 v[230:233], v[174:177], v[198:201], v[56:59]
	v_mfma_f32_16x16x32_bf16 v[56:59], v[136:139], v[202:205], v[84:87]
	v_mfma_f32_16x16x32_bf16 v[20:23], v[144:147], v[88:91], v[20:23]
	v_mfma_f32_16x16x32_bf16 v[32:35], v[174:177], v[88:91], v[32:35]
	v_mfma_f32_16x16x32_bf16 v[44:47], v[144:147], v[190:193], v[44:47]
	v_mfma_f32_16x16x32_bf16 v[136:139], v[144:147], v[208:211], v[56:59]
	v_mfma_f32_16x16x32_bf16 v[56:59], v[148:151], v[202:205], v[92:95]
	v_mfma_f32_16x16x32_bf16 v[144:147], v[174:177], v[208:211], v[56:59]
	v_mfma_f32_16x16x32_bf16 v[56:59], v[128:131], v[80:83], v[96:99]
	v_mfma_f32_16x16x32_bf16 v[148:151], v[140:143], v[88:91], v[56:59]
	v_mfma_f32_16x16x32_bf16 v[56:59], v[170:173], v[80:83], v[100:103]
	v_mfma_f32_16x16x32_bf16 v[174:177], v[218:221], v[88:91], v[56:59]
	v_mfma_f32_16x16x32_bf16 v[56:59], v[128:131], v[186:189], v[104:107]
	v_mfma_f32_16x16x32_bf16 v[234:237], v[140:143], v[190:193], v[56:59]
	v_mfma_f32_16x16x32_bf16 v[56:59], v[170:173], v[186:189], v[108:111]
	v_mfma_f32_16x16x32_bf16 v[186:189], v[218:221], v[190:193], v[56:59]
	v_mfma_f32_16x16x32_bf16 v[56:59], v[128:131], v[194:197], v[112:115]
	v_mfma_f32_16x16x32_bf16 v[190:193], v[140:143], v[198:201], v[56:59]
	v_mfma_f32_16x16x32_bf16 v[56:59], v[170:173], v[194:197], v[116:119]
	v_mfma_f32_16x16x32_bf16 v[194:197], v[218:221], v[198:201], v[56:59]
	v_mfma_f32_16x16x32_bf16 v[56:59], v[128:131], v[202:205], v[120:123]
	v_mfma_f32_16x16x32_bf16 v[128:131], v[140:143], v[208:211], v[56:59]
	v_mfma_f32_16x16x32_bf16 v[56:59], v[170:173], v[202:205], v[124:127]
	v_mfma_f32_16x16x32_bf16 v[140:143], v[218:221], v[208:211], v[56:59]
	s_barrier
	ds_read_b128 v[168:171], v166
	ds_read_b128 v[198:201], v166 offset:1024
	ds_read_b128 v[202:205], v166 offset:2048
	ds_read_b128 v[208:211], v166 offset:3072
	s_nop 1
	ds_read_b128 v[56:59], v163 offset:32768
	ds_read_b128 v[68:71], v163 offset:33792
	ds_read_b128 v[76:79], v162 offset:32768
	ds_read_b128 v[80:83], v162 offset:33792
	ds_read_b128 v[218:221], v161 offset:32768
	ds_read_b128 v[238:241], v161 offset:33792
	ds_read_b128 v[242:245], v160 offset:32768
	ds_read_b128 v[246:249], v160 offset:33792
	s_waitcnt vmcnt(2)
	s_barrier
	s_waitcnt lgkmcnt(0)
	s_waitcnt lgkmcnt(0)
	v_mfma_f32_16x16x32_bf16 v[0:3], v[168:171], v[56:59], v[0:3]
	v_mfma_f32_16x16x32_bf16 v[124:127], v[198:201], v[68:71], v[0:3]
	v_mfma_f32_16x16x32_bf16 v[0:3], v[202:205], v[56:59], v[4:7]
	v_mfma_f32_16x16x32_bf16 v[120:123], v[208:211], v[68:71], v[0:3]
	v_mfma_f32_16x16x32_bf16 v[0:3], v[168:171], v[76:79], v[8:11]
	v_mfma_f32_16x16x32_bf16 v[116:119], v[198:201], v[80:83], v[0:3]
	v_mfma_f32_16x16x32_bf16 v[0:3], v[202:205], v[76:79], v[16:19]
	v_mfma_f32_16x16x32_bf16 v[112:115], v[208:211], v[80:83], v[0:3]
	v_mfma_f32_16x16x32_bf16 v[0:3], v[168:171], v[218:221], v[28:31]
	v_mfma_f32_16x16x32_bf16 v[108:111], v[198:201], v[238:241], v[0:3]
	v_mfma_f32_16x16x32_bf16 v[0:3], v[202:205], v[218:221], v[40:43]
	v_mfma_f32_16x16x32_bf16 v[104:107], v[208:211], v[238:241], v[0:3]
	v_mfma_f32_16x16x32_bf16 v[0:3], v[168:171], v[242:245], v[52:55]
	v_mfma_f32_16x16x32_bf16 v[100:103], v[198:201], v[246:249], v[0:3]
	v_mfma_f32_16x16x32_bf16 v[0:3], v[202:205], v[242:245], v[64:67]
	v_mfma_f32_16x16x32_bf16 v[96:99], v[208:211], v[246:249], v[0:3]
	s_barrier
; #define UFOR(v, n) _Pragma("unroll") for (int v = 0; v < (n); ++v)
; #define LDA(dst, b, h) UFOR(m, 4) UFOR(k, 2) \
;     dst[m][k] = *reinterpret_cast<const bf16x8*>((char*)SA(b, h) + lds_byte(wr * 64 + m * 16 + fr, k * 32 + fq * 8))
; #define LDB(dst, b, h) UFOR(n, 2) UFOR(k, 2) \
;     dst[n][k] = *reinterpret_cast<const bf16x8*>((char*)SB(b, h) + lds_byte(wc * 32 + n * 16 + fr, k * 32 + fq * 8))
; #define MMA(ai, bj, At, Bq) do { __builtin_amdgcn_s_setprio(1); \
;     UFOR(m, 4) UFOR(n, 2) UFOR(k, 2) \
;       acc[ai][bj][m][n] = __builtin_amdgcn_mfma_f32_16x16x32_bf16(Bq[n][k], At[m][k], acc[ai][bj][m][n], 0, 0, 0); \
;     __builtin_amdgcn_s_setprio(0); } while (0)
; #define WAIT_V(n) asm volatile("s_waitcnt vmcnt(" #n ")" ::: "memory")
; #define WAIT_L(n) asm volatile("s_waitcnt lgkmcnt(" #n ")" ::: "memory")
; #define BAR __builtin_amdgcn_s_barrier()
; template <int EPI, int K, int KL> ...
;     ...
;   { LDB(B0, 1, 0); LDA(At, 1, 0); WAIT_V(2); BAR; WAIT_L(0); MMA(0, 0, At, B0); BAR;
;     LDB(B1, 1, 1); WAIT_V(0); BAR; WAIT_L(0); MMA(0, 1, At, B1); BAR;
;     LDA(At, 1, 1); BAR; WAIT_L(0); MMA(1, 0, At, B0); MMA(1, 1, At, B1); BAR; }
;   if (wr == 0) BAR;
;     ...
;       const int c4 = (tid_ & 31) * 4, rb = tid_ >> 5;
;       const int gc = pn * 128 + c4;
;       float wg[4][3], wv[4][3];
;       UFOR(q, 4) UFOR(x, 3) { wg[q][x] = e.cw[(size_t)(gc + q) * 3 + x]; wv[q][x] = e.cw[(size_t)(DFF + gc + q) * 3 + x]; }
	s_nop 5
	ds_read_b128 v[0:3], v164
	ds_read_b128 v[4:7], v164 offset:1024
	ds_read_b128 v[214:217], v164 offset:2048
	ds_read_b128 v[164:167], v164 offset:3072
	s_waitcnt vmcnt(0)
	s_barrier
	s_waitcnt lgkmcnt(0)
	s_waitcnt lgkmcnt(0)
	v_mfma_f32_16x16x32_bf16 v[8:11], v[0:3], v[56:59], v[12:15]
	v_mfma_f32_16x16x32_bf16 v[92:95], v[4:7], v[68:71], v[8:11]
	v_mfma_f32_16x16x32_bf16 v[8:11], v[214:217], v[56:59], v[24:27]
	v_mfma_f32_16x16x32_bf16 v[88:91], v[164:167], v[68:71], v[8:11]
	v_mfma_f32_16x16x32_bf16 v[8:11], v[0:3], v[76:79], v[36:39]
	v_mfma_f32_16x16x32_bf16 v[84:87], v[4:7], v[80:83], v[8:11]
	v_mfma_f32_16x16x32_bf16 v[8:11], v[214:217], v[76:79], v[48:51]
	v_mfma_f32_16x16x32_bf16 v[80:83], v[164:167], v[80:83], v[8:11]
	v_mfma_f32_16x16x32_bf16 v[8:11], v[0:3], v[218:221], v[60:63]
	v_mfma_f32_16x16x32_bf16 v[76:79], v[4:7], v[238:241], v[8:11]
	v_mfma_f32_16x16x32_bf16 v[8:11], v[214:217], v[218:221], v[72:75]
	v_mfma_f32_16x16x32_bf16 v[72:75], v[164:167], v[238:241], v[8:11]
	v_mfma_f32_16x16x32_bf16 v[8:11], v[0:3], v[242:245], v[178:181]
	v_mfma_f32_16x16x32_bf16 v[68:71], v[4:7], v[246:249], v[8:11]
	v_mfma_f32_16x16x32_bf16 v[8:11], v[214:217], v[242:245], v[182:185]
	v_mfma_f32_16x16x32_bf16 v[64:67], v[164:167], v[246:249], v[8:11]
	s_barrier
	s_nop 5
	ds_read_b128 v[8:11], v163 offset:49152
	ds_read_b128 v[12:15], v163 offset:50176
	ds_read_b128 v[16:19], v162 offset:49152
	ds_read_b128 v[178:181], v162 offset:50176
	ds_read_b128 v[182:185], v161 offset:49152
	ds_read_b128 v[218:221], v161 offset:50176
	ds_read_b128 v[238:241], v160 offset:49152
	ds_read_b128 v[158:161], v160 offset:50176
	s_barrier
	s_waitcnt lgkmcnt(0)
	s_waitcnt lgkmcnt(0)
	v_mfma_f32_16x16x32_bf16 v[20:23], v[168:171], v[8:11], v[20:23]
	v_mfma_f32_16x16x32_bf16 v[60:63], v[198:201], v[12:15], v[20:23]
	v_mfma_f32_16x16x32_bf16 v[20:23], v[202:205], v[8:11], v[32:35]
	v_mfma_f32_16x16x32_bf16 v[56:59], v[208:211], v[12:15], v[20:23]
	v_mfma_f32_16x16x32_bf16 v[20:23], v[168:171], v[16:19], v[44:47]
	v_mfma_f32_16x16x32_bf16 v[52:55], v[198:201], v[178:181], v[20:23]
	v_mfma_f32_16x16x32_bf16 v[20:23], v[202:205], v[16:19], v[222:225]
	v_mfma_f32_16x16x32_bf16 v[48:51], v[208:211], v[178:181], v[20:23]
	v_mfma_f32_16x16x32_bf16 v[20:23], v[168:171], v[182:185], v[226:229]
	v_mfma_f32_16x16x32_bf16 v[44:47], v[198:201], v[218:221], v[20:23]
	v_mfma_f32_16x16x32_bf16 v[20:23], v[202:205], v[182:185], v[230:233]
	v_mfma_f32_16x16x32_bf16 v[40:43], v[208:211], v[218:221], v[20:23]
	v_mfma_f32_16x16x32_bf16 v[20:23], v[168:171], v[238:241], v[136:139]
	v_mfma_f32_16x16x32_bf16 v[36:39], v[198:201], v[158:161], v[20:23]
	v_mfma_f32_16x16x32_bf16 v[20:23], v[202:205], v[238:241], v[144:147]
	v_mfma_f32_16x16x32_bf16 v[32:35], v[208:211], v[158:161], v[20:23]
	v_mfma_f32_16x16x32_bf16 v[20:23], v[0:3], v[8:11], v[148:151]
	v_mfma_f32_16x16x32_bf16 v[8:11], v[214:217], v[8:11], v[174:177]
	v_mfma_f32_16x16x32_bf16 v[24:27], v[164:167], v[12:15], v[8:11]
	v_mfma_f32_16x16x32_bf16 v[8:11], v[0:3], v[16:19], v[234:237]
	v_mfma_f32_16x16x32_bf16 v[28:31], v[4:7], v[12:15], v[20:23]
	v_mfma_f32_16x16x32_bf16 v[20:23], v[4:7], v[178:181], v[8:11]
	v_mfma_f32_16x16x32_bf16 v[8:11], v[214:217], v[16:19], v[186:189]
	v_mfma_f32_16x16x32_bf16 v[16:19], v[164:167], v[178:181], v[8:11]
	v_mfma_f32_16x16x32_bf16 v[8:11], v[0:3], v[182:185], v[190:193]
	v_mfma_f32_16x16x32_bf16 v[0:3], v[0:3], v[238:241], v[128:131]
	v_mfma_f32_16x16x32_bf16 v[12:15], v[4:7], v[218:221], v[8:11]
	v_mfma_f32_16x16x32_bf16 v[8:11], v[214:217], v[182:185], v[194:197]
	v_mfma_f32_16x16x32_bf16 v[4:7], v[4:7], v[158:161], v[0:3]
	v_mfma_f32_16x16x32_bf16 v[0:3], v[214:217], v[238:241], v[140:143]
	v_mfma_f32_16x16x32_bf16 v[8:11], v[164:167], v[218:221], v[8:11]
	v_mfma_f32_16x16x32_bf16 v[0:3], v[164:167], v[158:161], v[0:3]
	v_lshlrev_b32_e32 v242, 2, v152
	v_and_b32_e32 v242, 0x7c, v242
	v_lshl_or_b32 v242, s51, 7, v242
	v_add_u32_e32 v243, 0x1600, v242
	v_mad_i64_i32 v[244:245], vcc, v243, 12, s[46:47]
	v_mad_i64_i32 v[246:247], vcc, v242, 12, s[46:47]
	global_load_dwordx4 v[218:221], v[244:245], off offset:16
	global_load_dwordx4 v[222:225], v[244:245], off offset:32
	global_load_dwordx4 v[226:229], v[244:245], off
	global_load_dwordx4 v[230:233], v[246:247], off offset:16
	global_load_dwordx4 v[234:237], v[246:247], off offset:32
	global_load_dwordx4 v[238:241], v[246:247], off
	s_movk_i32 s40, 0x100
	v_cmp_gt_u32_e32 vcc, s40, v152
	s_barrier
	s_and_saveexec_b64 s[40:41], vcc
	s_cbranch_execz .LBB0_1110
	s_barrier
